# plus ctx_sb partial sums: 12 loads issued together
# baseline (speedup 1.0000x reference)
; __device__ __forceinline__ unsigned pk2(float lo, float hi) { unsigned r; asm("v_cvt_pk_bf16_f32 %0, %1, %2" : "=v"(r) : "v"(lo), "v"(hi)); return r; }
; __device__ __forceinline__ void ctx_sb_from_sctx(const Params& P) {
;     ...
;     for (int i = blockIdx.x * NTHR + threadIdx.x; i < 512 * D / 4; i += gridDim.x * NTHR) {
;         const int r = i / (D / 4), c4 = i - r * (D / 4); f32x4 v = *(const f32x4*)(SC + (size_t)i * 4);
; #pragma unroll
;         for (int s = 1; s < 12; ++s) v += *(const f32x4*)(SC + (size_t)s * 512 * D + (size_t)i * 4);
;         u32x2 o; o.x = pk2(v[0], v[1]); o.y = pk2(v[2], v[3]);
;         *(u32x2*)(SB + ((size_t)(r >> 8) * TPB + (r & 255)) * D + c4 * 4) = o; }
.LBB0_1010:
	v_ashrrev_i32_e32 v1, 31, v0
	v_lshl_add_u64 v[4:5], v[0:1], 4, s[28:29]
	global_load_dwordx4 v[20:23], v[4:5], off
	v_add_co_u32_e32 v16, vcc, 0x400000, v4
	s_nop 1
	v_addc_co_u32_e32 v17, vcc, 0, v5, vcc
	global_load_dwordx4 v[24:27], v[16:17], off
	v_add_co_u32_e32 v16, vcc, 0x800000, v4
	s_nop 1
	v_addc_co_u32_e32 v17, vcc, 0, v5, vcc
	global_load_dwordx4 v[28:31], v[16:17], off
	v_add_co_u32_e32 v16, vcc, 0xc00000, v4
	s_nop 1
	v_addc_co_u32_e32 v17, vcc, 0, v5, vcc
	global_load_dwordx4 v[32:35], v[16:17], off
	v_add_co_u32_e32 v16, vcc, 0x1000000, v4
	s_nop 1
	v_addc_co_u32_e32 v17, vcc, 0, v5, vcc
	global_load_dwordx4 v[36:39], v[16:17], off
	v_add_co_u32_e32 v16, vcc, 0x1400000, v4
	s_nop 1
	v_addc_co_u32_e32 v17, vcc, 0, v5, vcc
	global_load_dwordx4 v[40:43], v[16:17], off
	v_add_co_u32_e32 v16, vcc, 0x1800000, v4
	s_nop 1
	v_addc_co_u32_e32 v17, vcc, 0, v5, vcc
	global_load_dwordx4 v[44:47], v[16:17], off
	v_add_co_u32_e32 v16, vcc, 0x1c00000, v4
	s_nop 1
	v_addc_co_u32_e32 v17, vcc, 0, v5, vcc
	global_load_dwordx4 v[48:51], v[16:17], off
	v_add_co_u32_e32 v16, vcc, 0x2000000, v4
	s_nop 1
	v_addc_co_u32_e32 v17, vcc, 0, v5, vcc
	global_load_dwordx4 v[52:55], v[16:17], off
	v_add_co_u32_e32 v16, vcc, 0x2400000, v4
	s_nop 1
	v_addc_co_u32_e32 v17, vcc, 0, v5, vcc
	global_load_dwordx4 v[56:59], v[16:17], off
	v_add_co_u32_e32 v16, vcc, 0x2800000, v4
	s_nop 1
	v_addc_co_u32_e32 v17, vcc, 0, v5, vcc
	global_load_dwordx4 v[60:63], v[16:17], off
	v_add_co_u32_e32 v16, vcc, 0x2c00000, v4
	s_nop 1
	v_addc_co_u32_e32 v17, vcc, 0, v5, vcc
	global_load_dwordx4 v[64:67], v[16:17], off
	v_lshrrev_b32_e32 v1, 23, v1
	v_add_u32_e32 v1, v0, v1
	v_ashrrev_i32_e32 v1, 9, v1
	v_add_u32_e32 v0, s14, v0
	s_mov_b32 s8, 0x3ffff
	s_waitcnt vmcnt(10)
	v_pk_add_f32 v[10:11], v[20:21], v[24:25]
	v_pk_add_f32 v[12:13], v[22:23], v[26:27]
	s_waitcnt vmcnt(9)
	v_pk_add_f32 v[10:11], v[10:11], v[28:29]
	v_pk_add_f32 v[12:13], v[12:13], v[30:31]
	s_waitcnt vmcnt(8)
	v_pk_add_f32 v[10:11], v[10:11], v[32:33]
	v_pk_add_f32 v[12:13], v[12:13], v[34:35]
	s_waitcnt vmcnt(7)
	v_pk_add_f32 v[10:11], v[10:11], v[36:37]
	v_pk_add_f32 v[12:13], v[12:13], v[38:39]
	s_waitcnt vmcnt(6)
	v_pk_add_f32 v[10:11], v[10:11], v[40:41]
	v_pk_add_f32 v[12:13], v[12:13], v[42:43]
	s_waitcnt vmcnt(5)
	v_pk_add_f32 v[10:11], v[10:11], v[44:45]
	v_pk_add_f32 v[12:13], v[12:13], v[46:47]
	s_waitcnt vmcnt(4)
	v_pk_add_f32 v[10:11], v[10:11], v[48:49]
	v_pk_add_f32 v[12:13], v[12:13], v[50:51]
	s_waitcnt vmcnt(3)
	v_pk_add_f32 v[10:11], v[10:11], v[52:53]
	v_pk_add_f32 v[12:13], v[12:13], v[54:55]
	s_waitcnt vmcnt(2)
	v_pk_add_f32 v[10:11], v[10:11], v[56:57]
	v_pk_add_f32 v[12:13], v[12:13], v[58:59]
	s_waitcnt vmcnt(1)
	v_pk_add_f32 v[10:11], v[10:11], v[60:61]
	v_pk_add_f32 v[12:13], v[12:13], v[62:63]
	v_cmp_lt_i32_e32 vcc, s8, v0
	s_or_b64 s[6:7], vcc, s[6:7]
	s_waitcnt vmcnt(0)
	v_pk_add_f32 v[6:7], v[12:13], v[66:67]
	v_pk_add_f32 v[4:5], v[10:11], v[64:65]
	s_nop 0
	v_cvt_pk_bf16_f32 v4, v4, v5
	v_cvt_pk_bf16_f32 v5, v6, v7
	v_lshrrev_b32_e32 v6, 8, v1
	v_mul_i32_i24_e32 v6, 0x1100, v6
	v_ashrrev_i32_e32 v7, 31, v6
	v_and_or_b32 v6, v1, s92, v6
	v_lshlrev_b32_e32 v1, 11, v1
	v_lshlrev_b64 v[6:7], 12, v[6:7]
	v_sub_u32_e32 v8, v2, v1
	v_lshl_add_u64 v[6:7], s[38:39], 0, v[6:7]
	v_ashrrev_i32_e32 v9, 31, v8
	v_lshl_add_u64 v[6:7], v[8:9], 1, v[6:7]
	v_add_u32_e32 v2, s3, v2
	global_store_dwordx2 v[6:7], v[4:5], off
	s_andn2_b64 exec, exec, s[6:7]
	s_cbranch_execnz .LBB0_1010
